# c22 + pass C: redundant unit-end barrier removed (the two queue-fetch barriers already order the LDS reuse)
# baseline (speedup 1.0000x reference)
.LBB0_1112:
	s_cmpk_lt_i32 s67, 0x110
	s_mov_b32 s30, s67
	s_cbranch_scc0 .LBB0_1233

.LBB0_1298:
	s_andn2_b64 vcc, exec, s[4:5]
	s_mov_b32 s42, s71
	s_cbranch_vccz .LBB0_1400
